# adds: LN1 consumer wait counts allow the previous row's eight stores to stay in flight
# baseline (speedup 1.0000x reference)
.LBB0_706:
	s_or_b64 exec, exec, s[2:3]
	v_mov_b32_e32 v99, v103
	v_and_b32_e32 v1, 64, v175
	v_lshl_add_u64 v[124:125], s[6:7], 0, v[98:99]
	v_lshl_add_u64 v[126:127], s[94:95], 0, v[98:99]
	v_add_u32_e32 v98, 64, v1
	v_xor_b32_e32 v1, 1, v175
	v_cmp_lt_i32_e32 vcc, v1, v98
	v_xor_b32_e32 v99, 2, v175
	v_lshl_add_u64 v[122:123], s[28:29], 0, v[102:103]
	v_cndmask_b32_e32 v1, v175, v1, vcc
	v_cmp_lt_i32_e32 vcc, v99, v98
	v_lshlrev_b32_e32 v1, 2, v1
	s_sub_i32 s18, 0, s92
	v_cndmask_b32_e32 v99, v175, v99, vcc
	v_lshlrev_b32_e32 v172, 2, v99
	v_xor_b32_e32 v99, 4, v175
	v_cmp_lt_i32_e32 vcc, v99, v98
	s_mov_b64 s[2:3], 0
	s_mov_b32 s4, 0x3fb504f3
	v_cndmask_b32_e32 v99, v175, v99, vcc
	v_lshlrev_b32_e32 v173, 2, v99
	v_xor_b32_e32 v99, 8, v175
	v_cmp_lt_i32_e32 vcc, v99, v98
	v_mov_b32_e32 v178, 0x3727c5ac
	s_nop 0
	v_cndmask_b32_e32 v99, v175, v99, vcc
	v_lshlrev_b32_e32 v174, 2, v99
	v_xor_b32_e32 v99, 16, v175
	v_cmp_lt_i32_e32 vcc, v99, v98
	s_nop 1
	v_cndmask_b32_e32 v99, v175, v99, vcc
	v_lshlrev_b32_e32 v176, 2, v99
	v_xor_b32_e32 v99, 32, v175
	v_cmp_lt_i32_e32 vcc, v99, v98
	s_nop 1
	v_cndmask_b32_e32 v98, v175, v99, vcc
	v_lshlrev_b32_e32 v177, 2, v98
	s_waitcnt vmcnt(0)
	s_branch .LBB0_709

.LBB0_711:
	s_andn2_saveexec_b64 s[10:11], s[10:11]
	s_cbranch_execz .LBB0_713
	s_waitcnt vmcnt(15)
	v_and_b32_e32 v99, 0xffff0000, v104
	v_and_b32_e32 v101, 0xffff0000, v105
	v_lshlrev_b32_e32 v98, 16, v104
	v_lshlrev_b32_e32 v100, 16, v105
	v_pk_fma_f32 v[152:153], v[68:69], s[4:5], v[100:101] op_sel_hi:[1,0,1]
	v_pk_fma_f32 v[158:159], v[66:67], s[4:5], v[98:99] op_sel_hi:[1,0,1]
	s_waitcnt vmcnt(14)
	v_and_b32_e32 v99, 0xffff0000, v106
	v_and_b32_e32 v101, 0xffff0000, v107
	v_lshlrev_b32_e32 v98, 16, v106
	v_lshlrev_b32_e32 v100, 16, v107
	v_pk_fma_f32 v[148:149], v[72:73], s[4:5], v[100:101] op_sel_hi:[1,0,1]
	v_pk_fma_f32 v[150:151], v[70:71], s[4:5], v[98:99] op_sel_hi:[1,0,1]
	s_waitcnt vmcnt(13)
	v_and_b32_e32 v99, 0xffff0000, v108
	v_and_b32_e32 v101, 0xffff0000, v109
	v_lshlrev_b32_e32 v98, 16, v108
	v_lshlrev_b32_e32 v100, 16, v109
	v_pk_fma_f32 v[160:161], v[76:77], s[4:5], v[100:101] op_sel_hi:[1,0,1]
	v_pk_fma_f32 v[130:131], v[74:75], s[4:5], v[98:99] op_sel_hi:[1,0,1]
	s_waitcnt vmcnt(12)
	v_and_b32_e32 v99, 0xffff0000, v110
	v_and_b32_e32 v101, 0xffff0000, v111
	v_lshlrev_b32_e32 v98, 16, v110
	v_lshlrev_b32_e32 v100, 16, v111
	v_pk_fma_f32 v[128:129], v[80:81], s[4:5], v[100:101] op_sel_hi:[1,0,1]
	v_pk_fma_f32 v[134:135], v[78:79], s[4:5], v[98:99] op_sel_hi:[1,0,1]
	s_waitcnt vmcnt(11)
	v_and_b32_e32 v99, 0xffff0000, v112
	v_and_b32_e32 v101, 0xffff0000, v113
	v_lshlrev_b32_e32 v98, 16, v112
	v_lshlrev_b32_e32 v100, 16, v113
	v_pk_fma_f32 v[132:133], v[84:85], s[4:5], v[100:101] op_sel_hi:[1,0,1]
	v_pk_fma_f32 v[140:141], v[82:83], s[4:5], v[98:99] op_sel_hi:[1,0,1]
	s_waitcnt vmcnt(10)
	v_and_b32_e32 v99, 0xffff0000, v114
	v_and_b32_e32 v101, 0xffff0000, v115
	v_lshlrev_b32_e32 v98, 16, v114
	v_lshlrev_b32_e32 v100, 16, v115
	v_pk_fma_f32 v[168:169], v[88:89], s[4:5], v[100:101] op_sel_hi:[1,0,1]
	v_pk_fma_f32 v[138:139], v[86:87], s[4:5], v[98:99] op_sel_hi:[1,0,1]
	s_waitcnt vmcnt(9)
	v_and_b32_e32 v99, 0xffff0000, v116
	v_and_b32_e32 v101, 0xffff0000, v117
	v_lshlrev_b32_e32 v98, 16, v116
	v_lshlrev_b32_e32 v100, 16, v117
	v_pk_fma_f32 v[136:137], v[92:93], s[4:5], v[100:101] op_sel_hi:[1,0,1]
	v_pk_fma_f32 v[142:143], v[90:91], s[4:5], v[98:99] op_sel_hi:[1,0,1]
	s_waitcnt vmcnt(8)
	v_and_b32_e32 v99, 0xffff0000, v118
	v_and_b32_e32 v101, 0xffff0000, v119
	v_lshlrev_b32_e32 v98, 16, v118
	v_lshlrev_b32_e32 v100, 16, v119
	v_pk_fma_f32 v[100:101], v[96:97], s[4:5], v[100:101] op_sel_hi:[1,0,1]
	v_pk_fma_f32 v[98:99], v[94:95], s[4:5], v[98:99] op_sel_hi:[1,0,1]
	v_mov_b32_e32 v147, v158
	v_mov_b32_e32 v145, v152
	v_mov_b32_e32 v146, v150
	v_mov_b32_e32 v158, v151
	v_mov_b32_e32 v144, v148
	v_mov_b32_e32 v152, v149
	v_mov_b32_e32 v166, v131
	v_mov_b32_e32 v167, v160
	v_mov_b32_e32 v131, v161
	v_mov_b32_e32 v162, v141
	v_mov_b32_e32 v160, v133
	v_mov_b32_e32 v164, v139
	v_mov_b32_e32 v165, v168
	v_mov_b32_e32 v139, v169
	v_mov_b32_e32 v150, v99
	v_mov_b32_e32 v148, v101
.LBB0_713:
	s_or_b64 exec, exec, s[10:11]
	v_add_u32_e32 v168, s18, v120
	v_cmp_lt_i32_e32 vcc, -1, v168
	s_and_saveexec_b64 s[10:11], vcc
	s_cbranch_execz .LBB0_708
	s_movk_i32 s12, 0x203f
	v_cmp_lt_u32_e32 vcc, s12, v168
	s_and_saveexec_b64 s[12:13], vcc
	s_xor_b64 s[12:13], exec, s[12:13]
	s_cbranch_execz .LBB0_716
	s_waitcnt vmcnt(8)
	v_add_u32_e32 v66, 0xffffdfc0, v168
	v_mov_b32_e32 v67, v103
.LBB0_716:
	s_or_saveexec_b64 s[12:13], s[12:13]
	s_waitcnt vmcnt(8)
	v_mov_b64_e32 v[68:69], s[58:59]
	s_xor_b64 exec, exec, s[12:13]
	s_cbranch_execz .LBB0_722
	v_mul_u32_u24_e32 v66, 0x3f81, v168
	s_waitcnt vmcnt(8)
	v_lshrrev_b32_e32 v70, 25, v66
	v_mul_i32_i24_e32 v66, 0xfffff7f0, v70
	v_add3_u32 v66, s18, v66, v120
	v_cmp_lt_i32_e32 vcc, 15, v66
	v_mov_b64_e32 v[68:69], s[66:67]
	s_and_saveexec_b64 s[16:17], vcc
	s_xor_b64 s[16:17], exec, s[16:17]
	v_lshlrev_b32_e32 v68, 24, v70
	v_mov_b32_e32 v69, v103
	v_add_u32_e32 v66, -16, v66
	v_mov_b32_e32 v67, v103
	v_lshl_add_u64 v[68:69], s[56:57], 0, v[68:69]
	s_andn2_saveexec_b64 s[16:17], s[16:17]
	v_ashrrev_i32_e32 v67, 31, v66
	s_or_b64 exec, exec, s[16:17]
.LBB0_722:
	s_or_b64 exec, exec, s[12:13]
	v_lshlrev_b64 v[66:67], 13, v[66:67]
	v_lshl_add_u64 v[66:67], v[68:69], 0, v[66:67]
	s_waitcnt vmcnt(8)
	v_lshl_add_u64 v[82:83], v[66:67], 0, v[102:103]
	s_waitcnt vmcnt(8)
	v_add_co_u32_e32 v94, vcc, 0x1000, v82
	global_load_dwordx4 v[66:69], v[82:83], off nt
	global_load_dwordx4 v[70:73], v[82:83], off offset:1024 nt
	global_load_dwordx4 v[74:77], v[82:83], off offset:2048 nt
	global_load_dwordx4 v[78:81], v[82:83], off offset:3072 nt
	v_addc_co_u32_e32 v95, vcc, 0, v83, vcc
	global_load_dwordx4 v[82:85], v[94:95], off nt
	global_load_dwordx4 v[86:89], v[94:95], off offset:1024 nt
	global_load_dwordx4 v[90:93], v[94:95], off offset:2048 nt
	s_nop 0
	global_load_dwordx4 v[94:97], v[94:95], off offset:3072 nt
	v_cmp_gt_u32_e32 vcc, s5, v168
	s_and_saveexec_b64 s[12:13], vcc
	s_cbranch_execz .LBB0_707
	v_mov_b32_e32 v169, v103
	v_lshlrev_b64 v[104:105], 12, v[168:169]
	v_lshl_add_u64 v[118:119], v[124:125], 0, v[104:105]
	global_load_dwordx2 v[104:105], v[118:119], off nt
	global_load_dwordx2 v[106:107], v[118:119], off offset:512 nt
	global_load_dwordx2 v[108:109], v[118:119], off offset:1024 nt
	global_load_dwordx2 v[110:111], v[118:119], off offset:1536 nt
	global_load_dwordx2 v[112:113], v[118:119], off offset:2048 nt
	global_load_dwordx2 v[114:115], v[118:119], off offset:2560 nt
	global_load_dwordx2 v[116:117], v[118:119], off offset:3072 nt
	s_nop 0
	global_load_dwordx2 v[118:119], v[118:119], off offset:3584 nt
	s_branch .LBB0_707
